# phase_convert (phase 0 weight conversion) also replaced by the hand-written tile routine (masked columns for the 24-column job)
# speedup vs baseline: 1.0167x; 1.0014x over previous
.Lcl_last1:
	s_waitcnt vmcnt(0)
	ds_write2_b32 v7, v48, v49 offset0:0 offset1:4
	ds_write2_b32 v7, v50, v51 offset0:8 offset1:12
	ds_write2_b32 v7, v52, v53 offset0:16 offset1:20
	ds_write2_b32 v7, v54, v55 offset0:24 offset1:28
	ds_write2_b32 v7, v56, v57 offset0:32 offset1:36
	ds_write2_b32 v7, v58, v59 offset0:40 offset1:44
	ds_write2_b32 v7, v60, v61 offset0:48 offset1:52
	ds_write2_b32 v7, v62, v63 offset0:56 offset1:60
	s_waitcnt lgkmcnt(0)
	s_barrier
	ds_read2_b32 v[64:65], v10 offset0:0 offset1:1
	ds_read2_b32 v[66:67], v10 offset0:2 offset1:3
	ds_read2_b32 v[68:69], v10 offset0:4 offset1:5
	ds_read2_b32 v[70:71], v10 offset0:6 offset1:7
	ds_read2_b32 v[72:73], v11 offset0:0 offset1:1
	ds_read2_b32 v[74:75], v11 offset0:2 offset1:3
	ds_read2_b32 v[76:77], v11 offset0:4 offset1:5
	ds_read2_b32 v[78:79], v11 offset0:6 offset1:7
	s_waitcnt lgkmcnt(4)
	v_cvt_pk_bf16_f32 v80, v64, v65
	v_cvt_pk_bf16_f32 v81, v66, v67
	v_cvt_pk_bf16_f32 v82, v68, v69
	v_cvt_pk_bf16_f32 v83, v70, v71
	global_store_dwordx4 v16, v[80:83], s[22:23]
	s_waitcnt lgkmcnt(0)
	v_cvt_pk_bf16_f32 v84, v72, v73
	v_cvt_pk_bf16_f32 v85, v74, v75
	v_cvt_pk_bf16_f32 v86, v76, v77
	v_cvt_pk_bf16_f32 v87, v78, v79
	global_store_dwordx4 v17, v[84:87], s[22:23]
.Lcl_done:
	s_barrier
.LBB0_384:
	s_mov_b64 s[0:1], -1

.LBB0_455:
	s_andn2_b64 vcc, exec, s[0:1]
	s_cbranch_vccnz .LBB0_529
	v_readlane_b32 s6, v237, 0
	s_mov_b32 s7, s6
	s_mov_b32 s19, 0x10000
.Lce_entry:
	v_and_b32_e32 v2, 63, v163
	v_lshrrev_b32_e32 v3, 6, v163
	v_lshrrev_b32_e32 v4, 3, v163
	v_and_b32_e32 v5, 7, v163
	v_lshlrev_b32_e32 v5, 3, v5
	v_mul_u32_u24_e32 v18, 0x41, v2
	v_add_u32_e32 v18, v18, v3
	v_lshlrev_b32_e32 v6, 2, v18
	v_add_u32_e32 v7, 0x4100, v6
	v_mul_u32_u24_e32 v18, 0x41, v4
	v_add_u32_e32 v18, v18, v5
	v_lshlrev_b32_e32 v8, 2, v18
	v_add_u32_e32 v9, 0x2080, v8
	v_add_u32_e32 v10, 0x4100, v8
	v_add_u32_e32 v11, 0x4100, v9
	s_cmpk_ge_u32 s7, 1872
	s_cbranch_scc1 .Lce_done
	s_cmpk_lt_u32 s7, 832
	s_cbranch_scc1 .Lce_j0_0
	s_cmpk_lt_u32 s7, 1600
	s_cbranch_scc1 .Lce_j1_0
	s_cmpk_lt_u32 s7, 1616
	s_cbranch_scc1 .Lce_j2_0
	s_cmpk_lt_u32 s7, 1744
	s_cbranch_scc1 .Lce_j3_0
	v_readlane_b32 s8, v235, 22
	v_readlane_b32 s9, v235, 23
	s_mov_b32 s10, s76
	s_mov_b32 s11, s77
	s_mov_b32 s12, 0x400
	s_movk_i32 s13, 0x1080
	s_movk_i32 s16, 0
	s_add_u32 s10, s10, 0x108000
	s_addc_u32 s11, s11, 0
	s_movk_i32 s4, 256
	s_sub_u32 s17, s7, 1744
	s_and_b32 s14, s17, 31
	s_lshr_b32 s15, s17, 5
	s_branch .Lce_jc_0
.Lce_j0_0:
	v_readlane_b32 s8, v235, 18
	v_readlane_b32 s9, v235, 19
	s_mov_b32 s10, s46
	s_mov_b32 s11, s47
	s_mov_b32 s12, 0x6460
	s_movk_i32 s13, 0x880
	s_movk_i32 s16, 0
	s_movk_i32 s4, 3328
	s_mov_b32 s17, s7
	s_and_b32 s14, s17, 15
	s_lshr_b32 s15, s17, 4
	s_branch .Lce_jc_0
.Lce_j1_0:
	v_readlane_b32 s8, v235, 18
	v_readlane_b32 s9, v235, 19
	s_mov_b32 s10, s46
	s_mov_b32 s11, s47
	s_mov_b32 s12, 0x6460
	s_movk_i32 s13, 0x880
	s_movk_i32 s16, 0
	s_add_u32 s8, s8, 0x3460
	s_addc_u32 s9, s9, 0
	s_add_u32 s10, s10, 0x6e8000
	s_addc_u32 s11, s11, 0
	s_movk_i32 s4, 3072
	s_sub_u32 s17, s7, 832
	s_and_b32 s14, s17, 15
	s_lshr_b32 s15, s17, 4
	s_branch .Lce_jc_0
.Lce_j2_0:
	v_readlane_b32 s8, v235, 18
	v_readlane_b32 s9, v235, 19
	s_mov_b32 s10, s46
	s_mov_b32 s11, s47
	s_mov_b32 s12, 0x6460
	s_movk_i32 s13, 0x880
	s_movk_i32 s16, 0
	s_add_u32 s8, s8, 0x3400
	s_addc_u32 s9, s9, 0
	s_add_u32 s10, s10, 0xd48000
	s_addc_u32 s11, s11, 0
	s_movk_i32 s4, 24
	s_sub_u32 s17, s7, 1600
	s_and_b32 s14, s17, 15
	s_lshr_b32 s15, s17, 4
	s_branch .Lce_jc_0
.Lce_j3_0:
	v_readlane_b32 s8, v235, 20
	v_readlane_b32 s9, v235, 21
	s_mov_b32 s10, s76
	s_mov_b32 s11, s77
	s_mov_b32 s12, 0x400
	s_movk_i32 s13, 0x1080
	s_movk_i32 s16, 0
	s_movk_i32 s4, 256
	s_sub_u32 s17, s7, 1616
	s_and_b32 s14, s17, 31
	s_lshr_b32 s15, s17, 5
.Lce_jc_0:
	s_lshl_b32 s17, s14, 6
	s_mul_i32 s17, s17, s12
	s_add_u32 s8, s8, s17
	s_addc_u32 s9, s9, 0
	s_lshl_b32 s17, s15, 6
	s_mul_i32 s17, s17, s13
	s_lshl_b32 s18, s14, 7
	s_add_u32 s17, s17, s18
	s_add_u32 s10, s10, s17
	s_addc_u32 s11, s11, 0
	s_lshl_b32 s17, s15, 6
	v_add_u32_e32 v18, s17, v2
	v_mov_b32_e32 v22, v18
	v_add_u32_e32 v19, s17, v4
	v_cmp_gt_u32_e64 s[28:29], s4, v19
	v_add_u32_e32 v19, 32, v19
	v_cmp_gt_u32_e64 s[30:31], s4, v19
	v_mov_b32_e32 v32, 0
	v_mov_b32_e32 v33, 0
	v_mov_b32_e32 v34, 0
	v_mov_b32_e32 v35, 0
	v_mov_b32_e32 v36, 0
	v_mov_b32_e32 v37, 0
	v_mov_b32_e32 v38, 0
	v_mov_b32_e32 v39, 0
	v_mov_b32_e32 v40, 0
	v_mov_b32_e32 v41, 0
	v_mov_b32_e32 v42, 0
	v_mov_b32_e32 v43, 0
	v_mov_b32_e32 v44, 0
	v_mov_b32_e32 v45, 0
	v_mov_b32_e32 v46, 0
	v_mov_b32_e32 v47, 0
	v_bfe_u32 v19, v18, 5, 1
	v_mul_u32_u24_e32 v19, 0xb00, v19
	v_lshrrev_b32_e32 v20, 7, v18
	v_lshl_add_u32 v19, v20, 6, v19
	v_bfe_u32 v20, v18, 6, 1
	v_lshl_add_u32 v19, v20, 5, v19
	v_bfe_u32 v20, v18, 4, 1
	v_lshl_add_u32 v19, v20, 4, v19
	v_and_b32_e32 v20, 15, v18
	v_add_u32_e32 v19, v19, v20
	s_cmp_eq_u32 s16, 1
	s_cselect_b64 s[24:25], -1, 0
	s_nop 1
	v_cndmask_b32_e64 v18, v18, v19, s[24:25]
	v_mul_lo_u32 v19, v3, s12
	v_lshl_add_u32 v12, v18, 2, v19
	v_mul_lo_u32 v19, v4, s13
	v_lshl_add_u32 v14, v5, 1, v19
	s_lshl_b32 s17, s13, 5
	v_add_u32_e32 v15, s17, v14
	s_lshl_b32 s17, s12, 2
	v_cmp_gt_u32_e32 vcc, s4, v22
	s_and_saveexec_b64 s[26:27], vcc
	global_load_dword v32, v12, s[8:9]
	s_add_u32 s8, s8, s17
	s_addc_u32 s9, s9, 0
	global_load_dword v33, v12, s[8:9]
	s_add_u32 s8, s8, s17
	s_addc_u32 s9, s9, 0
	global_load_dword v34, v12, s[8:9]
	s_add_u32 s8, s8, s17
	s_addc_u32 s9, s9, 0
	global_load_dword v35, v12, s[8:9]
	s_add_u32 s8, s8, s17
	s_addc_u32 s9, s9, 0
	global_load_dword v36, v12, s[8:9]
	s_add_u32 s8, s8, s17
	s_addc_u32 s9, s9, 0
	global_load_dword v37, v12, s[8:9]
	s_add_u32 s8, s8, s17
	s_addc_u32 s9, s9, 0
	global_load_dword v38, v12, s[8:9]
	s_add_u32 s8, s8, s17
	s_addc_u32 s9, s9, 0
	global_load_dword v39, v12, s[8:9]
	s_add_u32 s8, s8, s17
	s_addc_u32 s9, s9, 0
	global_load_dword v40, v12, s[8:9]
	s_add_u32 s8, s8, s17
	s_addc_u32 s9, s9, 0
	global_load_dword v41, v12, s[8:9]
	s_add_u32 s8, s8, s17
	s_addc_u32 s9, s9, 0
	global_load_dword v42, v12, s[8:9]
	s_add_u32 s8, s8, s17
	s_addc_u32 s9, s9, 0
	global_load_dword v43, v12, s[8:9]
	s_add_u32 s8, s8, s17
	s_addc_u32 s9, s9, 0
	global_load_dword v44, v12, s[8:9]
	s_add_u32 s8, s8, s17
	s_addc_u32 s9, s9, 0
	global_load_dword v45, v12, s[8:9]
	s_add_u32 s8, s8, s17
	s_addc_u32 s9, s9, 0
	global_load_dword v46, v12, s[8:9]
	s_add_u32 s8, s8, s17
	s_addc_u32 s9, s9, 0
	global_load_dword v47, v12, s[8:9]
	s_mov_b64 exec, s[26:27]
.Lce_loop:
	s_addk_i32 s7, 0x200
	s_cmpk_ge_u32 s7, 1872
	s_cbranch_scc0 .Lce_nx0
	s_mov_b32 s7, s19
	s_mov_b32 s19, 0x10000
.Lce_nx0:
	s_cmpk_ge_u32 s7, 1872
	s_cbranch_scc1 .Lce_last0
	s_cmpk_lt_u32 s7, 832
	s_cbranch_scc1 .Lce_j0_1
	s_cmpk_lt_u32 s7, 1600
	s_cbranch_scc1 .Lce_j1_1
	s_cmpk_lt_u32 s7, 1616
	s_cbranch_scc1 .Lce_j2_1
	s_cmpk_lt_u32 s7, 1744
	s_cbranch_scc1 .Lce_j3_1
	v_readlane_b32 s20, v235, 22
	v_readlane_b32 s21, v235, 23
	s_mov_b32 s22, s76
	s_mov_b32 s23, s77
	s_mov_b32 s12, 0x400
	s_movk_i32 s13, 0x1080
	s_movk_i32 s16, 0
	s_add_u32 s22, s22, 0x108000
	s_addc_u32 s23, s23, 0
	s_movk_i32 s4, 256
	s_sub_u32 s17, s7, 1744
	s_and_b32 s14, s17, 31
	s_lshr_b32 s15, s17, 5
	s_branch .Lce_jc_1
.Lce_j0_1:
	v_readlane_b32 s20, v235, 18
	v_readlane_b32 s21, v235, 19
	s_mov_b32 s22, s46
	s_mov_b32 s23, s47
	s_mov_b32 s12, 0x6460
	s_movk_i32 s13, 0x880
	s_movk_i32 s16, 0
	s_movk_i32 s4, 3328
	s_mov_b32 s17, s7
	s_and_b32 s14, s17, 15
	s_lshr_b32 s15, s17, 4
	s_branch .Lce_jc_1
.Lce_j1_1:
	v_readlane_b32 s20, v235, 18
	v_readlane_b32 s21, v235, 19
	s_mov_b32 s22, s46
	s_mov_b32 s23, s47
	s_mov_b32 s12, 0x6460
	s_movk_i32 s13, 0x880
	s_movk_i32 s16, 0
	s_add_u32 s20, s20, 0x3460
	s_addc_u32 s21, s21, 0
	s_add_u32 s22, s22, 0x6e8000
	s_addc_u32 s23, s23, 0
	s_movk_i32 s4, 3072
	s_sub_u32 s17, s7, 832
	s_and_b32 s14, s17, 15
	s_lshr_b32 s15, s17, 4
	s_branch .Lce_jc_1
.Lce_j2_1:
	v_readlane_b32 s20, v235, 18
	v_readlane_b32 s21, v235, 19
	s_mov_b32 s22, s46
	s_mov_b32 s23, s47
	s_mov_b32 s12, 0x6460
	s_movk_i32 s13, 0x880
	s_movk_i32 s16, 0
	s_add_u32 s20, s20, 0x3400
	s_addc_u32 s21, s21, 0
	s_add_u32 s22, s22, 0xd48000
	s_addc_u32 s23, s23, 0
	s_movk_i32 s4, 24
	s_sub_u32 s17, s7, 1600
	s_and_b32 s14, s17, 15
	s_lshr_b32 s15, s17, 4
	s_branch .Lce_jc_1
.Lce_j3_1:
	v_readlane_b32 s20, v235, 20
	v_readlane_b32 s21, v235, 21
	s_mov_b32 s22, s76
	s_mov_b32 s23, s77
	s_mov_b32 s12, 0x400
	s_movk_i32 s13, 0x1080
	s_movk_i32 s16, 0
	s_movk_i32 s4, 256
	s_sub_u32 s17, s7, 1616
	s_and_b32 s14, s17, 31
	s_lshr_b32 s15, s17, 5
.Lce_jc_1:
	s_lshl_b32 s17, s14, 6
	s_mul_i32 s17, s17, s12
	s_add_u32 s20, s20, s17
	s_addc_u32 s21, s21, 0
	s_lshl_b32 s17, s15, 6
	s_mul_i32 s17, s17, s13
	s_lshl_b32 s18, s14, 7
	s_add_u32 s17, s17, s18
	s_add_u32 s22, s22, s17
	s_addc_u32 s23, s23, 0
	s_lshl_b32 s17, s15, 6
	v_add_u32_e32 v18, s17, v2
	v_mov_b32_e32 v22, v18
	v_add_u32_e32 v19, s17, v4
	v_cmp_gt_u32_e64 s[0:1], s4, v19
	v_add_u32_e32 v19, 32, v19
	v_cmp_gt_u32_e64 s[2:3], s4, v19
	v_mov_b32_e32 v48, 0
	v_mov_b32_e32 v49, 0
	v_mov_b32_e32 v50, 0
	v_mov_b32_e32 v51, 0
	v_mov_b32_e32 v52, 0
	v_mov_b32_e32 v53, 0
	v_mov_b32_e32 v54, 0
	v_mov_b32_e32 v55, 0
	v_mov_b32_e32 v56, 0
	v_mov_b32_e32 v57, 0
	v_mov_b32_e32 v58, 0
	v_mov_b32_e32 v59, 0
	v_mov_b32_e32 v60, 0
	v_mov_b32_e32 v61, 0
	v_mov_b32_e32 v62, 0
	v_mov_b32_e32 v63, 0
	v_bfe_u32 v19, v18, 5, 1
	v_mul_u32_u24_e32 v19, 0xb00, v19
	v_lshrrev_b32_e32 v20, 7, v18
	v_lshl_add_u32 v19, v20, 6, v19
	v_bfe_u32 v20, v18, 6, 1
	v_lshl_add_u32 v19, v20, 5, v19
	v_bfe_u32 v20, v18, 4, 1
	v_lshl_add_u32 v19, v20, 4, v19
	v_and_b32_e32 v20, 15, v18
	v_add_u32_e32 v19, v19, v20
	s_cmp_eq_u32 s16, 1
	s_cselect_b64 s[24:25], -1, 0
	s_nop 1
	v_cndmask_b32_e64 v18, v18, v19, s[24:25]
	v_mul_lo_u32 v19, v3, s12
	v_lshl_add_u32 v13, v18, 2, v19
	v_mul_lo_u32 v19, v4, s13
	v_lshl_add_u32 v16, v5, 1, v19
	s_lshl_b32 s17, s13, 5
	v_add_u32_e32 v17, s17, v16
	s_lshl_b32 s17, s12, 2
	v_cmp_gt_u32_e32 vcc, s4, v22
	s_and_saveexec_b64 s[26:27], vcc
	global_load_dword v48, v13, s[20:21]
	s_add_u32 s20, s20, s17
	s_addc_u32 s21, s21, 0
	global_load_dword v49, v13, s[20:21]
	s_add_u32 s20, s20, s17
	s_addc_u32 s21, s21, 0
	global_load_dword v50, v13, s[20:21]
	s_add_u32 s20, s20, s17
	s_addc_u32 s21, s21, 0
	global_load_dword v51, v13, s[20:21]
	s_add_u32 s20, s20, s17
	s_addc_u32 s21, s21, 0
	global_load_dword v52, v13, s[20:21]
	s_add_u32 s20, s20, s17
	s_addc_u32 s21, s21, 0
	global_load_dword v53, v13, s[20:21]
	s_add_u32 s20, s20, s17
	s_addc_u32 s21, s21, 0
	global_load_dword v54, v13, s[20:21]
	s_add_u32 s20, s20, s17
	s_addc_u32 s21, s21, 0
	global_load_dword v55, v13, s[20:21]
	s_add_u32 s20, s20, s17
	s_addc_u32 s21, s21, 0
	global_load_dword v56, v13, s[20:21]
	s_add_u32 s20, s20, s17
	s_addc_u32 s21, s21, 0
	global_load_dword v57, v13, s[20:21]
	s_add_u32 s20, s20, s17
	s_addc_u32 s21, s21, 0
	global_load_dword v58, v13, s[20:21]
	s_add_u32 s20, s20, s17
	s_addc_u32 s21, s21, 0
	global_load_dword v59, v13, s[20:21]
	s_add_u32 s20, s20, s17
	s_addc_u32 s21, s21, 0
	global_load_dword v60, v13, s[20:21]
	s_add_u32 s20, s20, s17
	s_addc_u32 s21, s21, 0
	global_load_dword v61, v13, s[20:21]
	s_add_u32 s20, s20, s17
	s_addc_u32 s21, s21, 0
	global_load_dword v62, v13, s[20:21]
	s_add_u32 s20, s20, s17
	s_addc_u32 s21, s21, 0
	global_load_dword v63, v13, s[20:21]
	s_mov_b64 exec, s[26:27]
	s_waitcnt vmcnt(16)
	ds_write2_b32 v6, v32, v33 offset0:0 offset1:4
	ds_write2_b32 v6, v34, v35 offset0:8 offset1:12
	ds_write2_b32 v6, v36, v37 offset0:16 offset1:20
	ds_write2_b32 v6, v38, v39 offset0:24 offset1:28
	ds_write2_b32 v6, v40, v41 offset0:32 offset1:36
	ds_write2_b32 v6, v42, v43 offset0:40 offset1:44
	ds_write2_b32 v6, v44, v45 offset0:48 offset1:52
	ds_write2_b32 v6, v46, v47 offset0:56 offset1:60
	s_waitcnt lgkmcnt(0)
	s_barrier
	ds_read2_b32 v[64:65], v8 offset0:0 offset1:1
	ds_read2_b32 v[66:67], v8 offset0:2 offset1:3
	ds_read2_b32 v[68:69], v8 offset0:4 offset1:5
	ds_read2_b32 v[70:71], v8 offset0:6 offset1:7
	ds_read2_b32 v[72:73], v9 offset0:0 offset1:1
	ds_read2_b32 v[74:75], v9 offset0:2 offset1:3
	ds_read2_b32 v[76:77], v9 offset0:4 offset1:5
	ds_read2_b32 v[78:79], v9 offset0:6 offset1:7
	s_waitcnt lgkmcnt(4)
	v_cvt_pk_bf16_f32 v80, v64, v65
	v_cvt_pk_bf16_f32 v81, v66, v67
	v_cvt_pk_bf16_f32 v82, v68, v69
	v_cvt_pk_bf16_f32 v83, v70, v71
	s_and_saveexec_b64 s[26:27], s[28:29]
	global_store_dwordx4 v14, v[80:83], s[10:11]
	s_mov_b64 exec, s[26:27]
	s_waitcnt lgkmcnt(0)
	v_cvt_pk_bf16_f32 v84, v72, v73
	v_cvt_pk_bf16_f32 v85, v74, v75
	v_cvt_pk_bf16_f32 v86, v76, v77
	v_cvt_pk_bf16_f32 v87, v78, v79
	s_and_saveexec_b64 s[26:27], s[30:31]
	global_store_dwordx4 v15, v[84:87], s[10:11]
	s_mov_b64 exec, s[26:27]
	s_addk_i32 s7, 0x200
	s_cmpk_ge_u32 s7, 1872
	s_cbranch_scc0 .Lce_nx1
	s_mov_b32 s7, s19
	s_mov_b32 s19, 0x10000
.Lce_nx1:
	s_cmpk_ge_u32 s7, 1872
	s_cbranch_scc1 .Lce_last1
	s_cmpk_lt_u32 s7, 832
	s_cbranch_scc1 .Lce_j0_2
	s_cmpk_lt_u32 s7, 1600
	s_cbranch_scc1 .Lce_j1_2
	s_cmpk_lt_u32 s7, 1616
	s_cbranch_scc1 .Lce_j2_2
	s_cmpk_lt_u32 s7, 1744
	s_cbranch_scc1 .Lce_j3_2
	v_readlane_b32 s8, v235, 22
	v_readlane_b32 s9, v235, 23
	s_mov_b32 s10, s76
	s_mov_b32 s11, s77
	s_mov_b32 s12, 0x400
	s_movk_i32 s13, 0x1080
	s_movk_i32 s16, 0
	s_add_u32 s10, s10, 0x108000
	s_addc_u32 s11, s11, 0
	s_movk_i32 s4, 256
	s_sub_u32 s17, s7, 1744
	s_and_b32 s14, s17, 31
	s_lshr_b32 s15, s17, 5
	s_branch .Lce_jc_2

.Lce_jc_2:
	s_lshl_b32 s17, s14, 6
	s_mul_i32 s17, s17, s12
	s_add_u32 s8, s8, s17
	s_addc_u32 s9, s9, 0
	s_lshl_b32 s17, s15, 6
	s_mul_i32 s17, s17, s13
	s_lshl_b32 s18, s14, 7
	s_add_u32 s17, s17, s18
	s_add_u32 s10, s10, s17
	s_addc_u32 s11, s11, 0
	s_lshl_b32 s17, s15, 6
	v_add_u32_e32 v18, s17, v2
	v_mov_b32_e32 v22, v18
	v_add_u32_e32 v19, s17, v4
	v_cmp_gt_u32_e64 s[28:29], s4, v19
	v_add_u32_e32 v19, 32, v19
	v_cmp_gt_u32_e64 s[30:31], s4, v19
	v_mov_b32_e32 v32, 0
	v_mov_b32_e32 v33, 0
	v_mov_b32_e32 v34, 0
	v_mov_b32_e32 v35, 0
	v_mov_b32_e32 v36, 0
	v_mov_b32_e32 v37, 0
	v_mov_b32_e32 v38, 0
	v_mov_b32_e32 v39, 0
	v_mov_b32_e32 v40, 0
	v_mov_b32_e32 v41, 0
	v_mov_b32_e32 v42, 0
	v_mov_b32_e32 v43, 0
	v_mov_b32_e32 v44, 0
	v_mov_b32_e32 v45, 0
	v_mov_b32_e32 v46, 0
	v_mov_b32_e32 v47, 0
	v_bfe_u32 v19, v18, 5, 1
	v_mul_u32_u24_e32 v19, 0xb00, v19
	v_lshrrev_b32_e32 v20, 7, v18
	v_lshl_add_u32 v19, v20, 6, v19
	v_bfe_u32 v20, v18, 6, 1
	v_lshl_add_u32 v19, v20, 5, v19
	v_bfe_u32 v20, v18, 4, 1
	v_lshl_add_u32 v19, v20, 4, v19
	v_and_b32_e32 v20, 15, v18
	v_add_u32_e32 v19, v19, v20
	s_cmp_eq_u32 s16, 1
	s_cselect_b64 s[24:25], -1, 0
	s_nop 1
	v_cndmask_b32_e64 v18, v18, v19, s[24:25]
	v_mul_lo_u32 v19, v3, s12
	v_lshl_add_u32 v12, v18, 2, v19
	v_mul_lo_u32 v19, v4, s13
	v_lshl_add_u32 v14, v5, 1, v19
	s_lshl_b32 s17, s13, 5
	v_add_u32_e32 v15, s17, v14
	s_lshl_b32 s17, s12, 2
	v_cmp_gt_u32_e32 vcc, s4, v22
	s_and_saveexec_b64 s[26:27], vcc
	global_load_dword v32, v12, s[8:9]
	s_add_u32 s8, s8, s17
	s_addc_u32 s9, s9, 0
	global_load_dword v33, v12, s[8:9]
	s_add_u32 s8, s8, s17
	s_addc_u32 s9, s9, 0
	global_load_dword v34, v12, s[8:9]
	s_add_u32 s8, s8, s17
	s_addc_u32 s9, s9, 0
	global_load_dword v35, v12, s[8:9]
	s_add_u32 s8, s8, s17
	s_addc_u32 s9, s9, 0
	global_load_dword v36, v12, s[8:9]
	s_add_u32 s8, s8, s17
	s_addc_u32 s9, s9, 0
	global_load_dword v37, v12, s[8:9]
	s_add_u32 s8, s8, s17
	s_addc_u32 s9, s9, 0
	global_load_dword v38, v12, s[8:9]
	s_add_u32 s8, s8, s17
	s_addc_u32 s9, s9, 0
	global_load_dword v39, v12, s[8:9]
	s_add_u32 s8, s8, s17
	s_addc_u32 s9, s9, 0
	global_load_dword v40, v12, s[8:9]
	s_add_u32 s8, s8, s17
	s_addc_u32 s9, s9, 0
	global_load_dword v41, v12, s[8:9]
	s_add_u32 s8, s8, s17
	s_addc_u32 s9, s9, 0
	global_load_dword v42, v12, s[8:9]
	s_add_u32 s8, s8, s17
	s_addc_u32 s9, s9, 0
	global_load_dword v43, v12, s[8:9]
	s_add_u32 s8, s8, s17
	s_addc_u32 s9, s9, 0
	global_load_dword v44, v12, s[8:9]
	s_add_u32 s8, s8, s17
	s_addc_u32 s9, s9, 0
	global_load_dword v45, v12, s[8:9]
	s_add_u32 s8, s8, s17
	s_addc_u32 s9, s9, 0
	global_load_dword v46, v12, s[8:9]
	s_add_u32 s8, s8, s17
	s_addc_u32 s9, s9, 0
	global_load_dword v47, v12, s[8:9]
	s_mov_b64 exec, s[26:27]
	s_waitcnt vmcnt(16)
	ds_write2_b32 v7, v48, v49 offset0:0 offset1:4
	ds_write2_b32 v7, v50, v51 offset0:8 offset1:12
	ds_write2_b32 v7, v52, v53 offset0:16 offset1:20
	ds_write2_b32 v7, v54, v55 offset0:24 offset1:28
	ds_write2_b32 v7, v56, v57 offset0:32 offset1:36
	ds_write2_b32 v7, v58, v59 offset0:40 offset1:44
	ds_write2_b32 v7, v60, v61 offset0:48 offset1:52
	ds_write2_b32 v7, v62, v63 offset0:56 offset1:60
	s_waitcnt lgkmcnt(0)
	s_barrier
	ds_read2_b32 v[64:65], v10 offset0:0 offset1:1
	ds_read2_b32 v[66:67], v10 offset0:2 offset1:3
	ds_read2_b32 v[68:69], v10 offset0:4 offset1:5
	ds_read2_b32 v[70:71], v10 offset0:6 offset1:7
	ds_read2_b32 v[72:73], v11 offset0:0 offset1:1
	ds_read2_b32 v[74:75], v11 offset0:2 offset1:3
	ds_read2_b32 v[76:77], v11 offset0:4 offset1:5
	ds_read2_b32 v[78:79], v11 offset0:6 offset1:7
	s_waitcnt lgkmcnt(4)
	v_cvt_pk_bf16_f32 v80, v64, v65
	v_cvt_pk_bf16_f32 v81, v66, v67
	v_cvt_pk_bf16_f32 v82, v68, v69
	v_cvt_pk_bf16_f32 v83, v70, v71
	s_and_saveexec_b64 s[26:27], s[0:1]
	global_store_dwordx4 v16, v[80:83], s[22:23]
	s_mov_b64 exec, s[26:27]
	s_waitcnt lgkmcnt(0)
	v_cvt_pk_bf16_f32 v84, v72, v73
	v_cvt_pk_bf16_f32 v85, v74, v75
	v_cvt_pk_bf16_f32 v86, v76, v77
	v_cvt_pk_bf16_f32 v87, v78, v79
	s_and_saveexec_b64 s[26:27], s[2:3]
	global_store_dwordx4 v17, v[84:87], s[22:23]
	s_mov_b64 exec, s[26:27]
	s_branch .Lce_loop
.Lce_last0:
	s_waitcnt vmcnt(0)
	ds_write2_b32 v6, v32, v33 offset0:0 offset1:4
	ds_write2_b32 v6, v34, v35 offset0:8 offset1:12
	ds_write2_b32 v6, v36, v37 offset0:16 offset1:20
	ds_write2_b32 v6, v38, v39 offset0:24 offset1:28
	ds_write2_b32 v6, v40, v41 offset0:32 offset1:36
	ds_write2_b32 v6, v42, v43 offset0:40 offset1:44
	ds_write2_b32 v6, v44, v45 offset0:48 offset1:52
	ds_write2_b32 v6, v46, v47 offset0:56 offset1:60
	s_waitcnt lgkmcnt(0)
	s_barrier
	ds_read2_b32 v[64:65], v8 offset0:0 offset1:1
	ds_read2_b32 v[66:67], v8 offset0:2 offset1:3
	ds_read2_b32 v[68:69], v8 offset0:4 offset1:5
	ds_read2_b32 v[70:71], v8 offset0:6 offset1:7
	ds_read2_b32 v[72:73], v9 offset0:0 offset1:1
	ds_read2_b32 v[74:75], v9 offset0:2 offset1:3
	ds_read2_b32 v[76:77], v9 offset0:4 offset1:5
	ds_read2_b32 v[78:79], v9 offset0:6 offset1:7
	s_waitcnt lgkmcnt(4)
	v_cvt_pk_bf16_f32 v80, v64, v65
	v_cvt_pk_bf16_f32 v81, v66, v67
	v_cvt_pk_bf16_f32 v82, v68, v69
	v_cvt_pk_bf16_f32 v83, v70, v71
	s_and_saveexec_b64 s[26:27], s[28:29]
	global_store_dwordx4 v14, v[80:83], s[10:11]
	s_mov_b64 exec, s[26:27]
	s_waitcnt lgkmcnt(0)
	v_cvt_pk_bf16_f32 v84, v72, v73
	v_cvt_pk_bf16_f32 v85, v74, v75
	v_cvt_pk_bf16_f32 v86, v76, v77
	v_cvt_pk_bf16_f32 v87, v78, v79
	s_and_saveexec_b64 s[26:27], s[30:31]
	global_store_dwordx4 v15, v[84:87], s[10:11]
	s_mov_b64 exec, s[26:27]
	s_branch .Lce_done
.Lce_last1:
	s_waitcnt vmcnt(0)
	ds_write2_b32 v7, v48, v49 offset0:0 offset1:4
	ds_write2_b32 v7, v50, v51 offset0:8 offset1:12
	ds_write2_b32 v7, v52, v53 offset0:16 offset1:20
	ds_write2_b32 v7, v54, v55 offset0:24 offset1:28
	ds_write2_b32 v7, v56, v57 offset0:32 offset1:36
	ds_write2_b32 v7, v58, v59 offset0:40 offset1:44
	ds_write2_b32 v7, v60, v61 offset0:48 offset1:52
	ds_write2_b32 v7, v62, v63 offset0:56 offset1:60
	s_waitcnt lgkmcnt(0)
	s_barrier
	ds_read2_b32 v[64:65], v10 offset0:0 offset1:1
	ds_read2_b32 v[66:67], v10 offset0:2 offset1:3
	ds_read2_b32 v[68:69], v10 offset0:4 offset1:5
	ds_read2_b32 v[70:71], v10 offset0:6 offset1:7
	ds_read2_b32 v[72:73], v11 offset0:0 offset1:1
	ds_read2_b32 v[74:75], v11 offset0:2 offset1:3
	ds_read2_b32 v[76:77], v11 offset0:4 offset1:5
	ds_read2_b32 v[78:79], v11 offset0:6 offset1:7
	s_waitcnt lgkmcnt(4)
	v_cvt_pk_bf16_f32 v80, v64, v65
	v_cvt_pk_bf16_f32 v81, v66, v67
	v_cvt_pk_bf16_f32 v82, v68, v69
	v_cvt_pk_bf16_f32 v83, v70, v71
	s_and_saveexec_b64 s[26:27], s[0:1]
	global_store_dwordx4 v16, v[80:83], s[22:23]
	s_mov_b64 exec, s[26:27]
	s_waitcnt lgkmcnt(0)
	v_cvt_pk_bf16_f32 v84, v72, v73
	v_cvt_pk_bf16_f32 v85, v74, v75
	v_cvt_pk_bf16_f32 v86, v76, v77
	v_cvt_pk_bf16_f32 v87, v78, v79
	s_and_saveexec_b64 s[26:27], s[2:3]
	global_store_dwordx4 v17, v[84:87], s[22:23]
	s_mov_b64 exec, s[26:27]
.Lce_done:
	s_barrier
	global_load_dword v8, v[164:165], off
	s_waitcnt vmcnt(0)
